# fused-norm consumers (P4 in-proj, P2 W1 at l=1): row sum-of-squares loads issued at the tile header instead of behind the next tile's DMA prefetch; on top of p4map
# baseline (speedup 1.0000x reference)
; #define WAIT_V(n) asm volatile("s_waitcnt vmcnt(" #n ")" ::: "memory")
; #define BAR __builtin_amdgcn_s_barrier()
; template <class Epi>
; DEVI void gemm_phase(const Params& p, const u16* __restrict__ A, const u16* __restrict__ Bt, const int M, const int N, const int K, const int Msplit, const Epi& epi) {
;     ...
;     f32x4 acc[2][2][4][2] = {};
;     bf16x8 At[4][2], B0[2][2], B1[2][2];
;     if (it == 0) { WAIT_V(0); } else { if constexpr (Epi::NST == 16) WAIT_V(16); else if constexpr (Epi::NST == 32) WAIT_V(32); else WAIT_V(0); }
;     if (wr == 1) BAR;
;     BAR;
;     BAR;
;     ...
;         nrm = epi.ssq != nullptr && brow < TL;
;         if (nrm) {
;           if (tid2 < 256) { const float* q = epi.ssq + brow + tid2; rl[tid2] = rsqrtf(((q[0] + q[T]) + (q[2 * T] + q[3 * T])) * (1.f / D) + 1e-6f); }
.LBB0_682:
	s_or_b64 exec, exec, s[12:13]
	s_lshl_b32 s90, s16, 8
	s_cmpk_gt_u32 s16, 0x7f
	s_cbranch_scc1 .Lmy_p2ssq_skip
	s_cmp_lg_u64 s[50:51], 0
	s_cbranch_scc0 .Lmy_p2ssq_skip
	s_cmpk_lt_u32 s33, 0x100
	s_cbranch_scc0 .Lmy_p2ssq_skip
	v_mbcnt_lo_u32_b32 v212, -1, 0
	v_mbcnt_hi_u32_b32 v212, -1, v212
	s_lshl_b64 s[30:31], s[90:91], 2
	v_readlane_b32 s32, v253, 47
	v_or_b32_e32 v212, s33, v212
	s_add_u32 s30, s32, s30
	v_readlane_b32 s32, v253, 48
	v_lshlrev_b32_e32 v212, 2, v212
	s_addc_u32 s31, s32, s31
	global_load_dword v237, v212, s[30:31]
	s_add_u32 s30, s30, 0x22000
	s_addc_u32 s31, s31, 0
	global_load_dword v238, v212, s[30:31]
	s_add_u32 s30, s30, 0x22000
	s_addc_u32 s31, s31, 0
	global_load_dword v239, v212, s[30:31]
	s_add_u32 s30, s30, 0x22000
	s_addc_u32 s31, s31, 0
	global_load_dword v245, v212, s[30:31]
.Lmy_p2ssq_skip:
	s_or_b32 s12, s90, 0x80
	s_mov_b32 s13, s91
	s_lshl_b32 s18, s17, 8
	s_lshl_b64 s[12:13], s[12:13], 11
	s_add_u32 s22, s68, s12
	s_mov_b32 s19, s91
	s_addc_u32 s23, s69, s13
	s_lshl_b64 s[12:13], s[18:19], 11
	s_add_u32 s19, s0, s12
	s_addc_u32 s41, s1, s13
	s_lshl_b64 s[12:13], s[90:91], 11
	s_add_u32 s42, s68, s12
	s_addc_u32 s43, s69, s13
	s_or_b32 s12, s18, 0x80
	s_mov_b32 s13, s91
	s_lshl_b64 s[12:13], s[12:13], 11
	s_add_u32 s48, s0, s12
	s_addc_u32 s49, s1, s13
	s_add_u32 s52, s22, 0x100
	s_mov_b32 s17, s91
	s_addc_u32 s53, s23, 0
	s_lshl_b64 s[12:13], s[16:17], 19
	v_readlane_b32 s17, v254, 50
	s_add_u32 s17, s17, s12
	v_readlane_b32 s12, v254, 51
	v_mov_b32_e32 v8, 0
	s_addc_u32 s56, s12, s13
	s_mov_b64 s[12:13], 0
	s_mov_b32 s57, -2
	v_mov_b32_e32 v9, v8
	v_mov_b32_e32 v10, v8
	v_mov_b32_e32 v11, v8
	v_mov_b32_e32 v12, v8
	v_mov_b32_e32 v13, v8
	v_mov_b32_e32 v14, v8
	v_mov_b32_e32 v15, v8
	v_mov_b32_e32 v16, v8
	v_mov_b32_e32 v17, v8
	v_mov_b32_e32 v18, v8
	v_mov_b32_e32 v19, v8
	v_mov_b32_e32 v20, v8
	v_mov_b32_e32 v21, v8
	v_mov_b32_e32 v22, v8
	v_mov_b32_e32 v23, v8
	v_mov_b32_e32 v24, v8
	v_mov_b32_e32 v25, v8
	v_mov_b32_e32 v26, v8
	v_mov_b32_e32 v27, v8
	v_mov_b32_e32 v28, v8
	v_mov_b32_e32 v29, v8
	v_mov_b32_e32 v30, v8
	v_mov_b32_e32 v31, v8
	v_mov_b32_e32 v32, v8
	v_mov_b32_e32 v33, v8
	v_mov_b32_e32 v34, v8
	v_mov_b32_e32 v35, v8
	v_mov_b32_e32 v36, v8
	v_mov_b32_e32 v37, v8
	v_mov_b32_e32 v38, v8
	v_mov_b32_e32 v39, v8
	v_mov_b32_e32 v40, v8
	v_mov_b32_e32 v41, v8
	v_mov_b32_e32 v42, v8
	v_mov_b32_e32 v43, v8
	v_mov_b32_e32 v44, v8
	v_mov_b32_e32 v45, v8
	v_mov_b32_e32 v46, v8
	v_mov_b32_e32 v47, v8
	v_mov_b32_e32 v48, v8
	v_mov_b32_e32 v49, v8
	v_mov_b32_e32 v50, v8
	v_mov_b32_e32 v51, v8
	v_mov_b32_e32 v52, v8
	v_mov_b32_e32 v53, v8
	v_mov_b32_e32 v54, v8
	v_mov_b32_e32 v55, v8
	v_mov_b32_e32 v56, v8
	v_mov_b32_e32 v57, v8
	v_mov_b32_e32 v58, v8
	v_mov_b32_e32 v59, v8
	v_mov_b32_e32 v60, v8
	v_mov_b32_e32 v61, v8
	v_mov_b32_e32 v62, v8
	v_mov_b32_e32 v63, v8
	v_mov_b32_e32 v64, v8
	v_mov_b32_e32 v65, v8
	v_mov_b32_e32 v66, v8
	v_mov_b32_e32 v67, v8
	v_mov_b32_e32 v68, v8
	v_mov_b32_e32 v69, v8
	v_mov_b32_e32 v70, v8
	v_mov_b32_e32 v71, v8
	v_mov_b32_e32 v72, v8
	v_mov_b32_e32 v73, v8
	v_mov_b32_e32 v74, v8
	v_mov_b32_e32 v75, v8
	v_mov_b32_e32 v76, v8
	v_mov_b32_e32 v77, v8
	v_mov_b32_e32 v78, v8
	v_mov_b32_e32 v79, v8
	v_mov_b32_e32 v80, v8
	v_mov_b32_e32 v81, v8
	v_mov_b32_e32 v82, v8
	v_mov_b32_e32 v83, v8
	v_mov_b32_e32 v84, v8
	v_mov_b32_e32 v85, v8
	v_mov_b32_e32 v86, v8
	v_mov_b32_e32 v87, v8
	v_mov_b32_e32 v88, v8
	v_mov_b32_e32 v89, v8
	v_mov_b32_e32 v90, v8
	v_mov_b32_e32 v91, v8
	v_mov_b32_e32 v92, v8
	v_mov_b32_e32 v93, v8
	v_mov_b32_e32 v94, v8
	v_mov_b32_e32 v95, v8
	v_mov_b32_e32 v96, v8
	v_mov_b32_e32 v97, v8
	v_mov_b32_e32 v98, v8
	v_mov_b32_e32 v99, v8
	v_mov_b32_e32 v100, v8
	v_mov_b32_e32 v101, v8
	v_mov_b32_e32 v102, v8
	v_mov_b32_e32 v103, v8
	v_mov_b32_e32 v104, v8
	v_mov_b32_e32 v105, v8
	v_mov_b32_e32 v106, v8
	v_mov_b32_e32 v107, v8
	v_mov_b32_e32 v108, v8
	v_mov_b32_e32 v109, v8
	v_mov_b32_e32 v110, v8
	v_mov_b32_e32 v111, v8
	v_mov_b32_e32 v112, v8
	v_mov_b32_e32 v113, v8
	v_mov_b32_e32 v114, v8
	v_mov_b32_e32 v115, v8
	v_mov_b32_e32 v116, v8
	v_mov_b32_e32 v117, v8
	v_mov_b32_e32 v118, v8
	v_mov_b32_e32 v119, v8
	v_mov_b32_e32 v120, v8
	v_mov_b32_e32 v121, v8
	v_mov_b32_e32 v122, v8
	v_mov_b32_e32 v123, v8
	v_mov_b32_e32 v124, v8
	v_mov_b32_e32 v125, v8
	v_mov_b32_e32 v126, v8
	v_mov_b32_e32 v127, v8
	v_mov_b32_e32 v128, v8
	v_mov_b32_e32 v129, v8
	v_mov_b32_e32 v130, v8
	v_mov_b32_e32 v131, v8
	v_mov_b32_e32 v132, v8
	v_mov_b32_e32 v133, v8
	v_mov_b32_e32 v134, v8
	v_mov_b32_e32 v135, v8
	s_barrier
	s_barrier

; #define WAIT_L(n) asm volatile("s_waitcnt lgkmcnt(" #n ")" ::: "memory")
; #define BAR __builtin_amdgcn_s_barrier()
; template <class Epi>
; DEVI void gemm_phase(const Params& p, const u16* __restrict__ A, const u16* __restrict__ Bt, const int M, const int N, const int K, const int Msplit, const Epi& epi) {
;     ...
;         nrm = epi.ssq != nullptr && brow < TL;
;         if (nrm) {
;           if (tid2 < 256) { const float* q = epi.ssq + brow + tid2; rl[tid2] = rsqrtf(((q[0] + q[T]) + (q[2 * T] + q[3 * T])) * (1.f / D) + 1e-6f); }
;           WAIT_L(0); BAR;
.LBB0_694:
	s_cmpk_lt_u32 s16, 0x80
	s_cselect_b64 s[10:11], -1, 0
	s_and_b64 s[12:13], s[50:51], s[10:11]
	v_cndmask_b32_e64 v136, 0, 1, s[12:13]
	v_mbcnt_lo_u32_b32 v142, -1, 0
	v_mbcnt_hi_u32_b32 v142, -1, v142
	v_cmp_ne_u32_e64 s[10:11], 1, v136
	s_andn2_b64 vcc, exec, s[12:13]
	v_or_b32_e32 v140, s33, v142
	s_cbranch_vccnz .LBB0_698
	s_movk_i32 s17, 0x100
	v_cmp_gt_i32_e32 vcc, s17, v140
	s_and_saveexec_b64 s[22:23], vcc
	s_cbranch_execz .LBB0_697
	s_and_b64 vcc, exec, s[8:9]
	s_cbranch_vccnz .Lmy_p2ssq_w0
	s_waitcnt vmcnt(14)
	s_branch .Lmy_p2ssq_wd

; template <class Epi>
; DEVI void gemm_phase(const Params& p, const u16* __restrict__ A, const u16* __restrict__ Bt, const int M, const int N, const int K, const int Msplit, const Epi& epi) {
;     ...
;           if (tid2 < 256) { const float* q = epi.ssq + brow + tid2; rl[tid2] = rsqrtf(((q[0] + q[T]) + (q[2 * T] + q[3 * T])) * (1.f / D) + 1e-6f); }
.Lmy_p2ssq_wd:
	v_add_f32_e32 v136, v237, v238
	v_add_f32_e32 v137, v239, v245
	s_nop 0
	v_add_f32_e32 v136, v136, v137
	v_fmamk_f32 v136, v136, 0x3a800000, v230
	v_cmp_gt_f32_e32 vcc, s28, v136
	v_mul_f32_e32 v137, 0x4b800000, v136
	s_nop 0
	v_cndmask_b32_e32 v136, v136, v137, vcc
	v_rsq_f32_e32 v136, v136
	s_nop 0
	v_mul_f32_e32 v137, 0x45800000, v136
	v_cndmask_b32_e32 v136, v136, v137, vcc
	v_lshl_add_u32 v137, v140, 2, 0
	ds_write_b32 v137, v136 offset:49152

; #define WAIT_V(n) asm volatile("s_waitcnt vmcnt(" #n ")" ::: "memory")
; #define BAR __builtin_amdgcn_s_barrier()
; template <class Epi>
; DEVI void gemm_phase(const Params& p, const u16* __restrict__ A, const u16* __restrict__ Bt, const int M, const int N, const int K, const int Msplit, const Epi& epi) {
;     ...
;     f32x4 acc[2][2][4][2] = {};
;     bf16x8 At[4][2], B0[2][2], B1[2][2];
;     if (it == 0) { WAIT_V(0); } else { if constexpr (Epi::NST == 16) WAIT_V(16); else if constexpr (Epi::NST == 32) WAIT_V(32); else WAIT_V(0); }
;     if (wr == 1) BAR;
;     BAR;
;     BAR;
;     ...
;         nrm = epi.ssq != nullptr && brow < TL;
;         if (nrm) {
;           if (tid2 < 256) { const float* q = epi.ssq + brow + tid2; rl[tid2] = rsqrtf(((q[0] + q[T]) + (q[2 * T] + q[3 * T])) * (1.f / D) + 1e-6f); }
.LBB0_1103:
	s_or_b64 exec, exec, s[14:15]
	s_lshl_b32 s36, s16, 8
	s_or_b32 s14, s36, 0x80
	s_ashr_i32 s15, s14, 31
	s_lshl_b32 s40, s17, 8
	s_lshl_b64 s[14:15], s[14:15], 11
	s_add_u32 s17, s68, s14
	s_addc_u32 s18, s69, s15
	s_ashr_i32 s41, s40, 31
	s_lshl_b64 s[14:15], s[40:41], 11
	s_add_u32 s19, s2, s14
	s_addc_u32 s20, s76, s15
	s_ashr_i32 s37, s36, 31
	s_lshl_b64 s[14:15], s[36:37], 11
	s_cmpk_gt_i32 s16, 0x7f
	s_cbranch_scc1 .Lmy_p4ssq_skip
	s_cmpk_lt_u32 s33, 0x100
	s_cbranch_scc0 .Lmy_p4ssq_skip
	v_mbcnt_lo_u32_b32 v226, -1, 0
	v_mbcnt_hi_u32_b32 v226, -1, v226
	s_lshl_b64 s[30:31], s[36:37], 2
	v_readlane_b32 s32, v255, 28
	v_or_b32_e32 v226, s33, v226
	s_add_u32 s30, s32, s30
	v_readlane_b32 s32, v255, 29
	v_lshlrev_b32_e32 v226, 2, v226
	s_addc_u32 s31, s32, s31
	global_load_dword v236, v226, s[30:31]
	s_add_u32 s30, s30, 0x22000
	s_addc_u32 s31, s31, 0
	global_load_dword v237, v226, s[30:31]
	s_add_u32 s30, s30, 0x22000
	s_addc_u32 s31, s31, 0
	global_load_dword v238, v226, s[30:31]
	s_add_u32 s30, s30, 0x22000
	s_addc_u32 s31, s31, 0
	global_load_dword v239, v226, s[30:31]
.Lmy_p4ssq_skip:
	s_add_u32 s21, s68, s14
	s_addc_u32 s22, s69, s15
	s_or_b32 s24, s40, 0x80
	s_ashr_i32 s25, s24, 31
	s_lshl_b64 s[24:25], s[24:25], 11
	s_add_u32 s23, s2, s24
	s_addc_u32 s24, s76, s25
	s_add_u32 s25, s17, 0x100
	s_addc_u32 s26, s18, 0
	v_readlane_b32 s27, v254, 50
	s_add_u32 s27, s27, s14
	v_readlane_b32 s14, v254, 51
	v_mov_b32_e32 v0, 0
	s_addc_u32 s41, s14, s15
	s_mov_b64 s[14:15], 0
	s_mov_b32 s42, -2
	v_mov_b32_e32 v1, v0
	v_mov_b32_e32 v2, v0
	v_mov_b32_e32 v3, v0
	v_mov_b32_e32 v4, v0
	v_mov_b32_e32 v5, v0
	v_mov_b32_e32 v6, v0
	v_mov_b32_e32 v7, v0
	v_mov_b32_e32 v8, v0
	v_mov_b32_e32 v9, v0
	v_mov_b32_e32 v10, v0
	v_mov_b32_e32 v11, v0
	v_mov_b32_e32 v12, v0
	v_mov_b32_e32 v13, v0
	v_mov_b32_e32 v14, v0
	v_mov_b32_e32 v15, v0
	v_mov_b32_e32 v16, v0
	v_mov_b32_e32 v17, v0
	v_mov_b32_e32 v18, v0
	v_mov_b32_e32 v19, v0
	v_mov_b32_e32 v20, v0
	v_mov_b32_e32 v21, v0
	v_mov_b32_e32 v22, v0
	v_mov_b32_e32 v23, v0
	v_mov_b32_e32 v24, v0
	v_mov_b32_e32 v25, v0
	v_mov_b32_e32 v26, v0
	v_mov_b32_e32 v27, v0
	v_mov_b32_e32 v28, v0
	v_mov_b32_e32 v29, v0
	v_mov_b32_e32 v30, v0
	v_mov_b32_e32 v31, v0
	v_mov_b32_e32 v32, v0
	v_mov_b32_e32 v33, v0
	v_mov_b32_e32 v34, v0
	v_mov_b32_e32 v35, v0
	v_mov_b32_e32 v36, v0
	v_mov_b32_e32 v37, v0
	v_mov_b32_e32 v38, v0
	v_mov_b32_e32 v39, v0
	v_mov_b32_e32 v40, v0
	v_mov_b32_e32 v41, v0
	v_mov_b32_e32 v42, v0
	v_mov_b32_e32 v43, v0
	v_mov_b32_e32 v44, v0
	v_mov_b32_e32 v45, v0
	v_mov_b32_e32 v46, v0
	v_mov_b32_e32 v47, v0
	v_mov_b32_e32 v48, v0
	v_mov_b32_e32 v49, v0
	v_mov_b32_e32 v50, v0
	v_mov_b32_e32 v51, v0
	v_mov_b32_e32 v52, v0
	v_mov_b32_e32 v53, v0
	v_mov_b32_e32 v54, v0
	v_mov_b32_e32 v55, v0
	v_mov_b32_e32 v56, v0
	v_mov_b32_e32 v57, v0
	v_mov_b32_e32 v58, v0
	v_mov_b32_e32 v59, v0
	v_mov_b32_e32 v60, v0
	v_mov_b32_e32 v61, v0
	v_mov_b32_e32 v62, v0
	v_mov_b32_e32 v63, v0
	v_mov_b32_e32 v64, v0
	v_mov_b32_e32 v65, v0
	v_mov_b32_e32 v66, v0
	v_mov_b32_e32 v67, v0
	v_mov_b32_e32 v68, v0
	v_mov_b32_e32 v69, v0
	v_mov_b32_e32 v70, v0
	v_mov_b32_e32 v71, v0
	v_mov_b32_e32 v72, v0
	v_mov_b32_e32 v73, v0
	v_mov_b32_e32 v74, v0
	v_mov_b32_e32 v75, v0
	v_mov_b32_e32 v76, v0
	v_mov_b32_e32 v77, v0
	v_mov_b32_e32 v78, v0
	v_mov_b32_e32 v79, v0
	v_mov_b32_e32 v80, v0
	v_mov_b32_e32 v81, v0
	v_mov_b32_e32 v82, v0
	v_mov_b32_e32 v83, v0
	v_mov_b32_e32 v84, v0
	v_mov_b32_e32 v85, v0
	v_mov_b32_e32 v86, v0
	v_mov_b32_e32 v87, v0
	v_mov_b32_e32 v88, v0
	v_mov_b32_e32 v89, v0
	v_mov_b32_e32 v90, v0
	v_mov_b32_e32 v91, v0
	v_mov_b32_e32 v92, v0
	v_mov_b32_e32 v93, v0
	v_mov_b32_e32 v94, v0
	v_mov_b32_e32 v95, v0
	v_mov_b32_e32 v96, v0
	v_mov_b32_e32 v97, v0
	v_mov_b32_e32 v98, v0
	v_mov_b32_e32 v99, v0
	v_mov_b32_e32 v100, v0
	v_mov_b32_e32 v101, v0
	v_mov_b32_e32 v102, v0
	v_mov_b32_e32 v103, v0
	v_mov_b32_e32 v104, v0
	v_mov_b32_e32 v105, v0
	v_mov_b32_e32 v106, v0
	v_mov_b32_e32 v107, v0
	v_mov_b32_e32 v108, v0
	v_mov_b32_e32 v109, v0
	v_mov_b32_e32 v110, v0
	v_mov_b32_e32 v111, v0
	v_mov_b32_e32 v112, v0
	v_mov_b32_e32 v113, v0
	v_mov_b32_e32 v114, v0
	v_mov_b32_e32 v115, v0
	v_mov_b32_e32 v116, v0
	v_mov_b32_e32 v117, v0
	v_mov_b32_e32 v118, v0
	v_mov_b32_e32 v119, v0
	v_mov_b32_e32 v120, v0
	v_mov_b32_e32 v121, v0
	v_mov_b32_e32 v122, v0
	v_mov_b32_e32 v123, v0
	v_mov_b32_e32 v124, v0
	v_mov_b32_e32 v125, v0
	v_mov_b32_e32 v126, v0
	v_mov_b32_e32 v127, v0
	s_barrier
	s_barrier

; #define WAIT_L(n) asm volatile("s_waitcnt lgkmcnt(" #n ")" ::: "memory")
; #define BAR __builtin_amdgcn_s_barrier()
; template <class Epi>
; DEVI void gemm_phase(const Params& p, const u16* __restrict__ A, const u16* __restrict__ Bt, const int M, const int N, const int K, const int Msplit, const Epi& epi) {
;     ...
;         nrm = epi.ssq != nullptr && brow < TL;
;         if (nrm) {
;           if (tid2 < 256) { const float* q = epi.ssq + brow + tid2; rl[tid2] = rsqrtf(((q[0] + q[T]) + (q[2 * T] + q[3 * T])) * (1.f / D) + 1e-6f); }
;           WAIT_L(0); BAR;
.LBB0_1115:
	s_cmpk_lt_i32 s16, 0x80
	v_mbcnt_lo_u32_b32 v128, -1, 0
	v_mbcnt_hi_u32_b32 v128, -1, v128
	s_cselect_b64 s[14:15], -1, 0
	s_cmpk_gt_i32 s16, 0x7f
	v_or_b32_e32 v134, s33, v128
	s_cbranch_scc1 .LBB0_1119
	v_cmp_gt_i32_e32 vcc, s28, v134
	s_and_saveexec_b64 s[12:13], vcc
	s_cbranch_execz .LBB0_1118
	s_and_b64 vcc, exec, s[10:11]
	s_cbranch_vccnz .Lmy_p4ssq_w0
	s_waitcnt vmcnt(14)
	s_branch .Lmy_p4ssq_wd

; template <class Epi>
; DEVI void gemm_phase(const Params& p, const u16* __restrict__ A, const u16* __restrict__ Bt, const int M, const int N, const int K, const int Msplit, const Epi& epi) {
;     ...
;           if (tid2 < 256) { const float* q = epi.ssq + brow + tid2; rl[tid2] = rsqrtf(((q[0] + q[T]) + (q[2 * T] + q[3 * T])) * (1.f / D) + 1e-6f); }
.Lmy_p4ssq_wd:
	v_add_f32_e32 v130, v236, v237
	v_add_f32_e32 v131, v238, v239
	s_nop 0
	v_add_f32_e32 v129, v130, v131
	v_fmamk_f32 v129, v129, 0x3a800000, v230
	v_cmp_gt_f32_e32 vcc, s63, v129
	v_mul_f32_e32 v130, 0x4b800000, v129
	s_nop 0
	v_cndmask_b32_e32 v129, v129, v130, vcc
	v_rsq_f32_e32 v129, v129
	s_nop 0
	v_mul_f32_e32 v130, 0x45800000, v129
	v_cndmask_b32_e32 v129, v129, v130, vcc
	v_lshl_add_u32 v130, v134, 2, 0
	ds_write_b32 v130, v129 offset:49152
